# ssd_pass2 final RMSNorm loop: the four (y, gain) load pairs of a row group requested together, one wait per group (was 4 x load-pair -> vmcnt(0) incl. previous store)
# baseline (speedup 1.0000x reference)
; __device__ __forceinline__ int ltid(int wv) { int l; asm volatile("v_mbcnt_lo_u32_b32 %0, -1, 0\n\tv_mbcnt_hi_u32_b32 %0, -1, %0" : "=v"(l)); asm volatile("" : "+s"(wv)); return (wv << 6) | l; }
; DI unsigned pk2(float lo, float hi) { const f32x2 v = {lo, hi}; const hwbf16x2 b = __builtin_convertvector(v, hwbf16x2); return __builtin_bit_cast(unsigned, b); }
; DI void ssd_pass2(LAS unsigned char* lds, const Args& a, const LayerP& P, int unit, int wv) {
;     ...
;     for (int g = 0; g < 2; ++g) { const int lane = ltid(wv) & 63, r = lane & 15, q = lane >> 4, h = 2 * g + hh;
; #pragma unroll
;         for (int ni = 0; ni < 2; ++ni) { const int l = lr + ni * 16 + r;
;             const float rs = __builtin_amdgcn_rsqf(((rowss[l] + rowss[128 + l]) + (rowss[256 + l] + rowss[384 + l])) * (1.0f / 256.0f) + EPS);
; #pragma unroll
;             for (int mi = 0; mi < 4; ++mi) { const int p0 = mi * 16 + 4 * q; const f32x4 y = *(const f32x4*)(YT + (size_t)(row0 + l) * 256 + h * 64 + p0), ng = *(const f32x4*)(P.ssd_ng + h * 64 + p0);
;                 u32x2 w; w.x = pk2(y[0] * rs * ng[0], y[1] * rs * ng[1]); w.y = pk2(y[2] * rs * ng[2], y[3] * rs * ng[3]);
;                 *(u32x2*)(Y + (size_t)(row0 + l) * DMODEL + 256 + h * 64 + p0) = w; } } }
.LBB0_1492:
	s_mov_b32 s3, s77
	v_mbcnt_lo_u32_b32 v0, -1, 0
	v_mbcnt_hi_u32_b32 v0, -1, v0
	s_add_i32 s58, s2, s5
	s_lshl_b64 s[2:3], s[58:59], 2
	s_add_u32 s18, s96, s2
	v_and_or_b32 v18, v0, 15, s30
	v_lshrrev_b32_e32 v0, 2, v0
	s_addc_u32 s19, s97, s3
	s_add_i32 s7, 0, 0x22800
	v_and_b32_e32 v19, 12, v0
	v_lshl_add_u32 v0, v18, 2, s7
	ds_read2st64_b32 v[2:3], v0 offset1:2
	ds_read2st64_b32 v[4:5], v0 offset0:4 offset1:6
	s_lshl_b64 s[20:21], s[58:59], 1
	s_add_u32 s2, s92, s2
	s_addc_u32 s3, s93, s3
	s_waitcnt lgkmcnt(1)
	v_mov_b32_e32 v6, v2
	s_waitcnt lgkmcnt(0)
	v_mov_b32_e32 v7, v4
	v_mov_b32_e32 v4, v3
	v_pk_add_f32 v[2:3], v[6:7], v[4:5]
	s_nop 0
	v_add_f32_e32 v0, v2, v3
	v_or_b32_e32 v2, s55, v18
	v_ashrrev_i32_e32 v3, 31, v2
	v_fmamk_f32 v0, v0, 0x3b800000, v202
	v_lshlrev_b64 v[6:7], 10, v[2:3]
	v_rsq_f32_e32 v4, v0
	v_lshl_add_u64 v[6:7], s[18:19], 0, v[6:7]
	v_lshlrev_b32_e32 v0, 2, v19
	v_lshl_add_u64 v[16:17], v[6:7], 0, v[0:1]
	global_load_dwordx4 v[6:9], v[16:17], off
	global_load_dwordx4 v[10:13], v0, s[2:3]
	global_load_dwordx4 v[108:111], v[16:17], off offset:64
	global_load_dwordx4 v[112:115], v0, s[2:3] offset:64
	global_load_dwordx4 v[116:119], v[16:17], off offset:128
	global_load_dwordx4 v[120:123], v0, s[2:3] offset:128
	global_load_dwordx4 v[124:127], v[16:17], off offset:192
	global_load_dwordx4 v[128:131], v0, s[2:3] offset:192
	v_lshlrev_b64 v[2:3], 11, v[2:3]
	v_lshl_add_u64 v[2:3], s[38:39], 0, v[2:3]
	v_lshl_add_u64 v[14:15], v[2:3], 0, s[20:21]
	s_waitcnt vmcnt(1)
	v_pk_mul_f32 v[2:3], v[6:7], v[4:5] op_sel_hi:[1,0]
	s_waitcnt vmcnt(0)
	v_pk_mul_f32 v[2:3], v[10:11], v[2:3]
	s_nop 0
	v_cvt_pk_bf16_f32 v6, v2, v3
	v_pk_mul_f32 v[2:3], v[8:9], v[4:5] op_sel_hi:[1,0]
	s_nop 0
	v_pk_mul_f32 v[2:3], v[12:13], v[2:3]
	s_nop 0
	v_cvt_pk_bf16_f32 v7, v2, v3
	v_lshlrev_b32_e32 v2, 1, v19
	v_mov_b32_e32 v3, v1
	v_lshl_add_u64 v[8:9], v[14:15], 0, v[2:3]
	v_lshl_add_u64 v[14:15], v[8:9], 0, s[80:81]
	v_add_co_u32_e32 v8, vcc, s79, v8
	s_nop 1
	v_addc_co_u32_e32 v9, vcc, 0, v9, vcc
	global_store_dwordx2 v[8:9], v[6:7], off offset:512
	v_mov_b32_e32 v6, v108
	v_mov_b32_e32 v7, v109
	v_mov_b32_e32 v8, v110
	v_mov_b32_e32 v9, v111
	s_nop 0
	v_mov_b32_e32 v10, v112
	v_mov_b32_e32 v11, v113
	v_mov_b32_e32 v12, v114
	v_mov_b32_e32 v13, v115
	s_nop 0
	v_pk_mul_f32 v[6:7], v[4:5], v[6:7] op_sel_hi:[0,1]
	v_pk_mul_f32 v[8:9], v[4:5], v[8:9] op_sel_hi:[0,1]
	s_nop 0
	v_pk_mul_f32 v[6:7], v[6:7], v[10:11]
	v_pk_mul_f32 v[8:9], v[8:9], v[12:13]
	v_cvt_pk_bf16_f32 v6, v6, v7
	v_cvt_pk_bf16_f32 v7, v8, v9
	global_store_dwordx2 v[14:15], v[6:7], off offset:32
	v_mov_b32_e32 v6, v116
	v_mov_b32_e32 v7, v117
	v_mov_b32_e32 v8, v118
	v_mov_b32_e32 v9, v119
	s_nop 0
	v_mov_b32_e32 v10, v120
	v_mov_b32_e32 v11, v121
	v_mov_b32_e32 v12, v122
	v_mov_b32_e32 v13, v123
	s_nop 0
	v_pk_mul_f32 v[6:7], v[4:5], v[6:7] op_sel_hi:[0,1]
	v_pk_mul_f32 v[8:9], v[4:5], v[8:9] op_sel_hi:[0,1]
	s_nop 0
	v_pk_mul_f32 v[6:7], v[6:7], v[10:11]
	v_pk_mul_f32 v[8:9], v[8:9], v[12:13]
	v_cvt_pk_bf16_f32 v6, v6, v7
	v_cvt_pk_bf16_f32 v7, v8, v9
	global_store_dwordx2 v[14:15], v[6:7], off offset:64
	v_mov_b32_e32 v6, v124
	v_mov_b32_e32 v7, v125
	v_mov_b32_e32 v8, v126
	v_mov_b32_e32 v9, v127
	s_nop 0
	v_mov_b32_e32 v10, v128
	v_mov_b32_e32 v11, v129
	v_mov_b32_e32 v12, v130
	v_mov_b32_e32 v13, v131
	s_nop 0
	v_pk_mul_f32 v[6:7], v[4:5], v[6:7] op_sel_hi:[0,1]
	v_pk_mul_f32 v[4:5], v[4:5], v[8:9] op_sel_hi:[0,1]
	s_nop 0
	v_pk_mul_f32 v[6:7], v[6:7], v[10:11]
	v_pk_mul_f32 v[4:5], v[4:5], v[12:13]
	v_cvt_pk_bf16_f32 v6, v6, v7
	v_cvt_pk_bf16_f32 v7, v4, v5
	v_or_b32_e32 v10, 16, v18
	global_store_dwordx2 v[14:15], v[6:7], off offset:96
	v_lshl_add_u32 v6, v10, 2, s7
	ds_read2st64_b32 v[4:5], v6 offset1:2
	ds_read2st64_b32 v[6:7], v6 offset0:4 offset1:6
	s_waitcnt lgkmcnt(1)
	v_mov_b32_e32 v8, v4
	s_waitcnt lgkmcnt(0)
	v_mov_b32_e32 v9, v6
	v_mov_b32_e32 v6, v5
	v_pk_add_f32 v[4:5], v[8:9], v[6:7]
	v_or_b32_e32 v6, s55, v10
	v_ashrrev_i32_e32 v7, 31, v6
	v_lshlrev_b64 v[8:9], 10, v[6:7]
	v_lshl_add_u64 v[8:9], s[18:19], 0, v[8:9]
	v_lshlrev_b64 v[6:7], 11, v[6:7]
	v_lshl_add_u64 v[6:7], s[38:39], 0, v[6:7]
	v_lshl_add_u64 v[16:17], v[8:9], 0, v[0:1]
	v_lshl_add_u64 v[14:15], v[6:7], 0, s[20:21]
	global_load_dwordx4 v[6:9], v[16:17], off
	global_load_dwordx4 v[10:13], v0, s[2:3]
	global_load_dwordx4 v[108:111], v[16:17], off offset:64
	global_load_dwordx4 v[112:115], v0, s[2:3] offset:64
	global_load_dwordx4 v[116:119], v[16:17], off offset:128
	global_load_dwordx4 v[120:123], v0, s[2:3] offset:128
	global_load_dwordx4 v[124:127], v[16:17], off offset:192
	global_load_dwordx4 v[128:131], v0, s[2:3] offset:192
	v_add_f32_e32 v4, v4, v5
	v_fmamk_f32 v4, v4, 0x3b800000, v202
	v_rsq_f32_e32 v4, v4
	v_lshl_add_u64 v[2:3], v[14:15], 0, v[2:3]
	v_lshl_add_u64 v[14:15], v[2:3], 0, s[80:81]
	v_add_co_u32_e32 v2, vcc, s79, v2
	s_waitcnt vmcnt(1)
	v_pk_mul_f32 v[6:7], v[6:7], v[4:5] op_sel_hi:[1,0]
	v_pk_mul_f32 v[8:9], v[8:9], v[4:5] op_sel_hi:[1,0]
	s_waitcnt vmcnt(0)
	v_pk_mul_f32 v[6:7], v[10:11], v[6:7]
	v_pk_mul_f32 v[8:9], v[12:13], v[8:9]
	v_cvt_pk_bf16_f32 v6, v6, v7
	v_cvt_pk_bf16_f32 v7, v8, v9
	v_addc_co_u32_e32 v3, vcc, 0, v3, vcc
	global_store_dwordx2 v[2:3], v[6:7], off offset:512
	v_mov_b32_e32 v6, v108
	v_mov_b32_e32 v7, v109
	v_mov_b32_e32 v8, v110
	v_mov_b32_e32 v9, v111
	s_nop 0
	v_mov_b32_e32 v10, v112
	v_mov_b32_e32 v11, v113
	v_mov_b32_e32 v12, v114
	v_mov_b32_e32 v13, v115
	s_and_b64 vcc, exec, s[16:17]
	s_mov_b64 s[16:17], 0
	s_nop 0
	v_pk_mul_f32 v[2:3], v[4:5], v[6:7] op_sel_hi:[0,1]
	v_pk_mul_f32 v[6:7], v[4:5], v[8:9] op_sel_hi:[0,1]
	s_nop 0
	v_pk_mul_f32 v[2:3], v[2:3], v[10:11]
	v_pk_mul_f32 v[6:7], v[6:7], v[12:13]
	v_cvt_pk_bf16_f32 v2, v2, v3
	v_cvt_pk_bf16_f32 v3, v6, v7
	global_store_dwordx2 v[14:15], v[2:3], off offset:32
	v_mov_b32_e32 v6, v116
	v_mov_b32_e32 v7, v117
	v_mov_b32_e32 v8, v118
	v_mov_b32_e32 v9, v119
	v_mov_b32_e32 v10, v120
	v_mov_b32_e32 v11, v121
	v_mov_b32_e32 v12, v122
	v_mov_b32_e32 v13, v123
	s_nop 0
	v_pk_mul_f32 v[2:3], v[4:5], v[6:7] op_sel_hi:[0,1]
	v_pk_mul_f32 v[6:7], v[4:5], v[8:9] op_sel_hi:[0,1]
	s_nop 0
	v_pk_mul_f32 v[2:3], v[2:3], v[10:11]
	v_pk_mul_f32 v[6:7], v[6:7], v[12:13]
	v_cvt_pk_bf16_f32 v2, v2, v3
	v_cvt_pk_bf16_f32 v3, v6, v7
	global_store_dwordx2 v[14:15], v[2:3], off offset:64
	v_mov_b32_e32 v6, v124
	v_mov_b32_e32 v7, v125
	v_mov_b32_e32 v8, v126
	v_mov_b32_e32 v9, v127
	v_mov_b32_e32 v10, v128
	v_mov_b32_e32 v11, v129
	v_mov_b32_e32 v12, v130
	v_mov_b32_e32 v13, v131
	s_movk_i32 s2, 0x80
	s_nop 0
	v_pk_mul_f32 v[2:3], v[4:5], v[6:7] op_sel_hi:[0,1]
	v_pk_mul_f32 v[4:5], v[4:5], v[8:9] op_sel_hi:[0,1]
	s_nop 0
	v_pk_mul_f32 v[2:3], v[2:3], v[10:11]
	v_pk_mul_f32 v[4:5], v[4:5], v[12:13]
	v_cvt_pk_bf16_f32 v2, v2, v3
	v_cvt_pk_bf16_f32 v3, v4, v5
	global_store_dwordx2 v[14:15], v[2:3], off offset:96
	s_cbranch_vccnz .LBB0_1492
	s_add_i32 s34, s34, s60
	s_cmpk_gt_i32 s34, 0xff
	s_cbranch_scc0 .LBB0_1365
